# scan: qe/ke written channel-permuted so qe@S fragments are single ds_read_b128; step flush moved behind the staging writes; on top of the B2/C rewrite and P0 silu batching
# speedup vs baseline: 1.0228x; 1.0040x over previous
; __device__ __forceinline__ int v_st(int k, int c) { const int kk = (k & ~0xC) | ((k & 4) << 1) | ((k & 8) >> 1); return ((kk >> 3) * 4 + (c >> 5)) * 512 + ((kk & 7) * 32 + (c & 31)) * 2; }
; #define OPAQUE_TID(name) int name = MK_TID; asm volatile("" : "+v"(name))
; __device__ __forceinline__ void scan_unit(const int unit, const Args& a, unsigned char* lds, const int mk_wid) {
;     ...
;         { OPAQUE_TID(t_);
; #pragma unroll
;           for (int p = 0; p < 2; ++p) { const int i_ = p * 32 + (t_ >> 4), c_ = (t_ & 15) * 8; *(bf16x8*)(qe + i_ * QP + c_) = qraw[p]; *(bf16x8*)(ke + i_ * QP + c_) = kraw[p]; }
; #pragma unroll
;           for (int p = 0; p < 4; ++p) { const int i_ = p * 16 + (t_ >> 5), c8 = t_ & 31; *(bf16x8*)(lds + L_V + (c8 >> 4) * 16384 + v_st(i_, (c8 & 15) * 8)) = vraw[p]; }
;           if (t_ < 128) *(bf16x8*)(lds + L_LR + (t_ >> 1) * 32 + (t_ & 1) * 16) = lraw; }
.LBB0_418:
	v_mbcnt_lo_u32_b32 v64, -1, 0
	v_mbcnt_hi_u32_b32 v64, -1, v64
	s_nop 0
	v_add_u32_e32 v64, s72, v64
	s_nop 0
	v_lshlrev_b32_e32 v66, 3, v64
	v_lshrrev_b32_e32 v65, 4, v64
	v_and_b32_e32 v67, 0x78, v66
	v_lshlrev_b32_e32 v67, 1, v67
	v_mul_lo_u32 v65, v65, s51
	v_add3_u32 v65, 0, v67, v65
	s_waitcnt vmcnt(5)
	ds_write_b128 v65, v[128:131]
	ds_write_b128 v65, v[100:103] offset:17408
	s_waitcnt vmcnt(4)
	ds_write_b128 v65, v[132:135] offset:8704
	ds_write_b128 v65, v[104:107] offset:26112
	v_ashrrev_i32_e32 v65, 5, v64
	v_lshlrev_b32_e32 v68, 10, v64
	v_lshrrev_b32_e32 v69, 1, v65
	v_and_b32_e32 v70, 3, v65
	v_and_b32_e32 v68, 0x4000, v68
	v_and_or_b32 v69, v69, 4, v70
	v_add_u32_e32 v68, 0, v68
	v_lshlrev_b32_e32 v69, 6, v69
	v_and_b32_e32 v67, 48, v67
	v_add3_u32 v67, v68, v69, v67
	v_and_b32_e32 v68, 0xfffff0, v65
	v_lshlrev_b32_e32 v69, 1, v65
	v_and_or_b32 v68, v69, 8, v68
	v_bfe_u32 v66, v66, 5, 2
	v_lshrrev_b32_e32 v68, 1, v68
	v_or_b32_e32 v68, v68, v66
	v_lshl_add_u32 v68, v68, 9, v67
	s_waitcnt vmcnt(3)
	ds_write_b128 v68, v[112:115] offset:51200
	v_add_u32_e32 v68, 16, v65
	v_and_b32_e32 v69, 0xfffff0, v68
	v_lshlrev_b32_e32 v68, 1, v68
	v_and_or_b32 v68, v68, 8, v69
	v_lshrrev_b32_e32 v68, 1, v68
	v_or_b32_e32 v68, v68, v66
	v_lshl_add_u32 v68, v68, 9, v67
	s_waitcnt vmcnt(2)
	ds_write_b128 v68, v[116:119] offset:51200
	v_add_u32_e32 v68, 32, v65
	v_and_b32_e32 v69, 0xfffff0, v68
	v_lshlrev_b32_e32 v68, 1, v68
	v_and_or_b32 v68, v68, 8, v69
	v_lshrrev_b32_e32 v68, 1, v68
	v_or_b32_e32 v68, v68, v66
	v_lshl_add_u32 v68, v68, 9, v67
	v_add_u32_e32 v65, 48, v65
	s_waitcnt vmcnt(1)
	ds_write_b128 v68, v[120:123] offset:51200
	v_and_b32_e32 v68, 0xfffff0, v65
	v_lshlrev_b32_e32 v65, 1, v65
	v_and_or_b32 v65, v65, 8, v68
	v_lshrrev_b32_e32 v65, 1, v65
	v_or_b32_e32 v65, v65, v66
	v_lshl_add_u32 v65, v65, 9, v67
	v_cmp_gt_i32_e32 vcc, s52, v64
	s_waitcnt vmcnt(0)
	ds_write_b128 v65, v[124:127] offset:51200
	s_and_saveexec_b64 s[26:27], vcc
	v_lshlrev_b32_e32 v64, 4, v64
	v_and_b32_e32 v65, 0xffffffe0, v64
	v_and_b32_e32 v64, 16, v64
	v_add3_u32 v64, s53, v65, v64
	ds_write_b128 v64, v[96:99]
	s_or_b64 exec, exec, s[26:27]
	s_cmp_lt_i32 s34, 0
	s_cbranch_scc1 .Lscan_noflush
	v_mbcnt_lo_u32_b32 v64, -1, 0
	v_mbcnt_hi_u32_b32 v64, -1, v64
	s_ashr_i32 s35, s34, 31
	v_add_u32_e32 v76, s72, v64
	s_lshl_b64 s[26:27], s[34:35], 6
	v_lshlrev_b32_e32 v64, 4, v76
	s_add_u32 s4, s26, s20
	v_and_b32_e32 v154, 0x1f0, v64
	v_ashrrev_i32_e32 v68, 5, v76
	s_addc_u32 s27, s27, s21
	v_add_u32_e32 v77, s9, v154
	v_sub_u32_e32 v69, 63, v68
	s_add_u32 s26, s4, 0xffffff00
	v_lshl_add_u32 v64, v68, 9, v77
	v_cndmask_b32_e64 v68, v69, v68, s[2:3]
	s_addc_u32 s27, s27, -1
	v_ashrrev_i32_e32 v69, 31, v68
	ds_read_b128 v[64:67], v64
	v_lshl_add_u64 v[68:69], s[26:27], 0, v[68:69]
	v_lshl_add_u64 v[72:73], s[18:19], 0, v[154:155]
	v_lshlrev_b64 v[68:69], 11, v[68:69]
	v_lshl_add_u64 v[74:75], v[72:73], 0, v[68:69]
	v_add_u32_e32 v68, 0x200, v76
	v_ashrrev_i32_e32 v78, 5, v68
	v_lshl_add_u32 v68, v78, 9, v77
	ds_read_b128 v[68:71], v68
	s_waitcnt lgkmcnt(1)
	global_store_dwordx4 v[74:75], v[64:67], off
	s_nop 1
	v_sub_u32_e32 v64, 63, v78
	v_cndmask_b32_e64 v64, v64, v78, s[2:3]
	v_ashrrev_i32_e32 v65, 31, v64
	v_lshl_add_u64 v[64:65], s[26:27], 0, v[64:65]
	v_lshlrev_b64 v[64:65], 11, v[64:65]
	v_lshl_add_u64 v[64:65], v[72:73], 0, v[64:65]
	s_waitcnt lgkmcnt(0)
	global_store_dwordx4 v[64:65], v[68:71], off
	v_add_u32_e32 v64, 0x400, v76
	s_nop 0
	v_ashrrev_i32_e32 v68, 5, v64
	v_sub_u32_e32 v69, 63, v68
	v_lshl_add_u32 v64, v68, 9, v77
	v_cndmask_b32_e64 v68, v69, v68, s[2:3]
	v_ashrrev_i32_e32 v69, 31, v68
	ds_read_b128 v[64:67], v64
	v_lshl_add_u64 v[68:69], s[26:27], 0, v[68:69]
	v_lshlrev_b64 v[68:69], 11, v[68:69]
	v_lshl_add_u64 v[74:75], v[72:73], 0, v[68:69]
	v_add_u32_e32 v68, 0x600, v76
	v_ashrrev_i32_e32 v76, 5, v68
	v_lshl_add_u32 v68, v76, 9, v77
	ds_read_b128 v[68:71], v68
	s_waitcnt lgkmcnt(1)
	global_store_dwordx4 v[74:75], v[64:67], off
	s_nop 1
	v_sub_u32_e32 v64, 63, v76
	v_cndmask_b32_e64 v64, v64, v76, s[2:3]
	v_ashrrev_i32_e32 v65, 31, v64
	v_lshl_add_u64 v[64:65], s[26:27], 0, v[64:65]
	v_lshlrev_b64 v[64:65], 11, v[64:65]
	v_lshl_add_u64 v[64:65], v[72:73], 0, v[64:65]
	s_waitcnt lgkmcnt(0)
	global_store_dwordx4 v[64:65], v[68:71], off
; __device__ __forceinline__ int crow(int r, int hi) { return (r & 3) + 8 * (r >> 2) + 4 * hi; }
; #define OPAQUE_TID(name) int name = MK_TID; asm volatile("" : "+v"(name))
; __device__ __forceinline__ void scan_unit(const int unit, const Args& a, unsigned char* lds, const int mk_wid) {
;     ...
;         __syncthreads();
;         { OPAQUE_TID(t_); const int lane = t_ & 63, r32 = lane & 31, hi = lane >> 5; const int tt = wid >> 2, ct = wid & 3;
;           const bf16x8 af = *(const bf16x8*)(lds + L_LR + (tt * 32 + r32) * 32 + hi * 16);
;           const f32x16 z = __builtin_amdgcn_mfma_f32_32x32x16_bf16(af, upf, f32x16{}, 0, 0, 0);
;           float* lw = las + (tt * 32 + 4 * hi) * 128 + ct * 32 + r32;
; #pragma unroll
;           for (int r = 0; r < 16; ++r) { const float zz = z[r] + biasc;
;               lw[crow(r, 0) * 128] = (fminf(zz, 0.f) - __builtin_amdgcn_logf(1.f + __builtin_amdgcn_exp2f(-1.4426950408889634f * fabsf(zz))) * 0.6931471805599453f) * (1.f / 16.f); } }
;         __syncthreads();
.Lscan_noflush:
	s_waitcnt lgkmcnt(0)
	s_barrier
	v_mbcnt_lo_u32_b32 v64, -1, 0
	v_mbcnt_hi_u32_b32 v64, -1, v64
	s_nop 0
	v_add_u32_e32 v64, s72, v64
	s_nop 0
	v_and_b32_e32 v68, 31, v64
	v_bfe_u32 v69, v64, 5, 1
	v_lshlrev_b32_e32 v64, 5, v68
	v_lshlrev_b32_e32 v65, 4, v69
	v_add3_u32 v64, s44, v64, v65
	ds_read_b128 v[64:67], v64
	v_lshlrev_b32_e32 v69, 11, v69
	v_lshlrev_b32_e32 v68, 2, v68
	v_add3_u32 v80, s45, v69, v68
	s_waitcnt lgkmcnt(0)
	v_mfma_f32_32x32x16_bf16 v[64:79], v[64:67], v[108:111], 0
	s_nop 11
	v_add_f32_e32 v64, v156, v64
	v_add_f32_e32 v65, v156, v65
	v_mul_f32_e64 v81, |v64|, s54
	v_mul_f32_e64 v82, |v65|, s54
	v_exp_f32_e32 v81, v81
	v_exp_f32_e32 v82, v82
	v_add_f32_e32 v66, v156, v66
	v_min_f32_e32 v64, 0, v64
	v_add_f32_e32 v81, 1.0, v81
	v_add_f32_e32 v82, 1.0, v82
	v_log_f32_e32 v81, v81
	v_log_f32_e32 v82, v82
	v_min_f32_e32 v65, 0, v65
	v_mul_f32_e64 v83, |v66|, s54
	v_fmac_f32_e32 v64, 0xbf317218, v81
	v_fmac_f32_e32 v65, 0xbf317218, v82
	v_add_f32_e32 v67, v156, v67
	v_exp_f32_e32 v83, v83
	v_mul_f32_e32 v64, 0x3d800000, v64
	v_mul_f32_e32 v65, 0x3d800000, v65
	ds_write2st64_b32 v80, v64, v65 offset1:2
	v_mul_f32_e64 v64, |v67|, s54
	v_exp_f32_e32 v64, v64
	v_add_f32_e32 v65, 1.0, v83
	v_log_f32_e32 v65, v65
	v_min_f32_e32 v66, 0, v66
	v_add_f32_e32 v64, 1.0, v64
	v_log_f32_e32 v64, v64
	v_fmac_f32_e32 v66, 0xbf317218, v65
	v_mul_f32_e32 v65, 0x3d800000, v66
	v_min_f32_e32 v66, 0, v67
	v_fmac_f32_e32 v66, 0xbf317218, v64
	v_mul_f32_e32 v64, 0x3d800000, v66
	ds_write2st64_b32 v80, v65, v64 offset0:4 offset1:6
	v_add_f32_e32 v64, v156, v68
	v_mul_f32_e64 v65, |v64|, s54
	v_add_f32_e32 v66, v156, v69
	v_exp_f32_e32 v65, v65
	v_mul_f32_e64 v67, |v66|, s54
	v_exp_f32_e32 v67, v67
	v_min_f32_e32 v64, 0, v64
	v_add_f32_e32 v65, 1.0, v65
	v_log_f32_e32 v65, v65
	v_add_f32_e32 v67, 1.0, v67
	v_log_f32_e32 v67, v67
	v_fmac_f32_e32 v64, 0xbf317218, v65
	v_min_f32_e32 v65, 0, v66
	v_fmac_f32_e32 v65, 0xbf317218, v67
	v_mul_f32_e32 v64, 0x3d800000, v64
	v_mul_f32_e32 v65, 0x3d800000, v65
	ds_write2st64_b32 v80, v64, v65 offset0:16 offset1:18
	v_add_f32_e32 v64, v156, v70
	v_mul_f32_e64 v65, |v64|, s54
	v_add_f32_e32 v66, v156, v71
	v_exp_f32_e32 v65, v65
	v_mul_f32_e64 v67, |v66|, s54
	v_exp_f32_e32 v67, v67
	v_min_f32_e32 v64, 0, v64
	v_add_f32_e32 v65, 1.0, v65
	v_log_f32_e32 v65, v65
	v_add_f32_e32 v67, 1.0, v67
	v_log_f32_e32 v67, v67
	v_fmac_f32_e32 v64, 0xbf317218, v65
	v_min_f32_e32 v65, 0, v66
	v_fmac_f32_e32 v65, 0xbf317218, v67
	v_mul_f32_e32 v64, 0x3d800000, v64
	v_mul_f32_e32 v65, 0x3d800000, v65
	ds_write2st64_b32 v80, v64, v65 offset0:20 offset1:22
	v_add_f32_e32 v64, v156, v72
	v_mul_f32_e64 v65, |v64|, s54
	v_add_f32_e32 v66, v156, v73
	v_exp_f32_e32 v65, v65
	v_mul_f32_e64 v67, |v66|, s54
	v_exp_f32_e32 v67, v67
	v_min_f32_e32 v64, 0, v64
	v_add_f32_e32 v65, 1.0, v65
	v_log_f32_e32 v65, v65
	v_add_f32_e32 v67, 1.0, v67
	v_log_f32_e32 v67, v67
	v_fmac_f32_e32 v64, 0xbf317218, v65
	v_min_f32_e32 v65, 0, v66
	v_fmac_f32_e32 v65, 0xbf317218, v67
	v_mul_f32_e32 v64, 0x3d800000, v64
	v_mul_f32_e32 v65, 0x3d800000, v65
	ds_write2st64_b32 v80, v64, v65 offset0:32 offset1:34
	v_add_f32_e32 v64, v156, v74
	v_mul_f32_e64 v65, |v64|, s54
	v_add_f32_e32 v66, v156, v75
	v_exp_f32_e32 v65, v65
	v_mul_f32_e64 v67, |v66|, s54
	v_exp_f32_e32 v67, v67
	v_min_f32_e32 v64, 0, v64
	v_add_f32_e32 v65, 1.0, v65
	v_log_f32_e32 v65, v65
	v_add_f32_e32 v67, 1.0, v67
	v_log_f32_e32 v67, v67
	v_fmac_f32_e32 v64, 0xbf317218, v65
	v_min_f32_e32 v65, 0, v66
	v_fmac_f32_e32 v65, 0xbf317218, v67
	v_mul_f32_e32 v64, 0x3d800000, v64
	v_mul_f32_e32 v65, 0x3d800000, v65
	ds_write2st64_b32 v80, v64, v65 offset0:36 offset1:38
	v_add_f32_e32 v64, v156, v76
	v_mul_f32_e64 v65, |v64|, s54
	v_add_f32_e32 v66, v156, v77
	v_exp_f32_e32 v65, v65
	v_mul_f32_e64 v67, |v66|, s54
	v_exp_f32_e32 v67, v67
	v_min_f32_e32 v64, 0, v64
	v_add_f32_e32 v65, 1.0, v65
	v_log_f32_e32 v65, v65
	v_add_f32_e32 v67, 1.0, v67
	v_log_f32_e32 v67, v67
	v_fmac_f32_e32 v64, 0xbf317218, v65
	v_min_f32_e32 v65, 0, v66
	v_fmac_f32_e32 v65, 0xbf317218, v67
	v_mul_f32_e32 v64, 0x3d800000, v64
	v_mul_f32_e32 v65, 0x3d800000, v65
	ds_write2st64_b32 v80, v64, v65 offset0:48 offset1:50
	v_add_f32_e32 v64, v156, v78
	v_mul_f32_e64 v65, |v64|, s54
	v_add_f32_e32 v66, v156, v79
	v_exp_f32_e32 v65, v65
	v_mul_f32_e64 v67, |v66|, s54
	v_exp_f32_e32 v67, v67
	v_min_f32_e32 v64, 0, v64
	v_add_f32_e32 v65, 1.0, v65
	v_log_f32_e32 v65, v65
	v_add_f32_e32 v67, 1.0, v67
	v_log_f32_e32 v67, v67
	v_fmac_f32_e32 v64, 0xbf317218, v65
	v_min_f32_e32 v65, 0, v66
	v_fmac_f32_e32 v65, 0xbf317218, v67
	v_mul_f32_e32 v64, 0x3d800000, v64
	v_mul_f32_e32 v65, 0x3d800000, v65
	ds_write2st64_b32 v80, v64, v65 offset0:52 offset1:54
	s_waitcnt lgkmcnt(0)
	s_barrier
; __device__ __forceinline__ int v_st(int k, int c) { const int kk = (k & ~0xC) | ((k & 4) << 1) | ((k & 8) >> 1); return ((kk >> 3) * 4 + (c >> 5)) * 512 + ((kk & 7) * 32 + (c & 31)) * 2; }
; __device__ __forceinline__ float bf2f(short s) { return __uint_as_float(((unsigned)(unsigned short)s) << 16); }
; __device__ __forceinline__ float bf2f(u16 u) { return __uint_as_float((unsigned)u << 16); }
; #define OPAQUE_TID(name) int name = MK_TID; asm volatile("" : "+v"(name))
; __device__ __forceinline__ void scan_unit(const int unit, const Args& a, unsigned char* lds, const int mk_wid) {
;     ...
;         { OPAQUE_TID(t_); const int c = t_ & 127, g = t_ >> 7;
;           float bl[16]; float run = 0.f;
;           { const float* lp = las + (g * 16) * 128 + c;
; #pragma unroll
;             for (int ii = 0; ii < 16; ++ii) { run += lp[ii * 128]; bl[ii] = run; } }
;           gs[g * 128 + c] = run;
;           __syncthreads();
;           const float g0 = gs[c], g1 = gs[128 + c], g2 = gs[256 + c], g3 = gs[384 + c];
;           const float off = (g > 0 ? g0 : 0.f) + (g > 1 ? g1 : 0.f) + (g > 2 ? g2 : 0.f);
;           const float btot = (g0 + g1) + (g2 + g3);
;           const float dlc = __builtin_amdgcn_exp2f(btot * 1.4426950408889634f);
;           if (g == 0) dl[c] = dlc;
;           u16* qcol = qe + (g * 16) * QP + c; u16* kcol = ke + (g * 16) * QP + c; unsigned char* kdb = lds + L_KD + v_st(g * 16, c);
; #pragma unroll
;           for (int ii = 0; ii < 16; ++ii) { const float bb = bl[ii] + off;
;               const float qf = bf2f(qcol[ii * QP]), kf = bf2f(kcol[ii * QP]);
;               const float e = __builtin_amdgcn_exp2f(bb * 1.4426950408889634f), ker = kf * __builtin_amdgcn_rcpf(e);
	v_mbcnt_lo_u32_b32 v64, -1, 0
	v_mbcnt_hi_u32_b32 v64, -1, v64
	s_lshl_b32 s96, s70, 12
	s_add_i32 s96, s96, s9
	v_lshl_add_u32 v65, v64, 3, s96
	ds_read_b64 v[170:171], v65
	ds_read_b64 v[172:173], v65 offset:512
	ds_read_b64 v[174:175], v65 offset:1024
	ds_read_b64 v[176:177], v65 offset:1536
	ds_read_b64 v[178:179], v65 offset:2048
	ds_read_b64 v[180:181], v65 offset:2560
	ds_read_b64 v[182:183], v65 offset:3072
	ds_read_b64 v[184:185], v65 offset:3584
	s_cmp_gt_u32 s70, 0
	s_cselect_b32 s97, 1.0, 0
	v_mov_b32_e32 v238, s97
	s_cmp_gt_u32 s70, 1
	s_cselect_b32 s97, 1.0, 0
	v_mov_b32_e32 v239, s97
	s_cmp_gt_u32 s70, 2
	s_cselect_b32 s97, 1.0, 0
	v_mov_b32_e32 v240, s97
	s_cmp_gt_u32 s70, 3
	s_cselect_b32 s97, 1.0, 0
	v_mov_b32_e32 v241, s97
	s_cmp_gt_u32 s70, 4
	s_cselect_b32 s97, 1.0, 0
	v_mov_b32_e32 v242, s97
	s_cmp_gt_u32 s70, 5
	s_cselect_b32 s97, 1.0, 0
	v_mov_b32_e32 v243, s97
	s_cmp_gt_u32 s70, 6
	s_cselect_b32 s97, 1.0, 0
	v_mov_b32_e32 v244, s97
	s_lshl_b32 s98, s70, 9
	s_add_i32 s98, s98, 0x20000
	v_lshl_add_u32 v66, v64, 3, s98
	v_lshlrev_b32_e32 v67, 3, v64
	v_add_u32_e32 v67, 0x20000, v67
	s_mul_i32 s99, s70, 0x880
	v_lshl_add_u32 v68, v64, 2, s99
	v_and_b32_e32 v94, 2, v64
	v_lshlrev_b32_e32 v94, 1, v94
	v_and_b32_e32 v95, 4, v64
	v_lshrrev_b32_e32 v95, 1, v95
	v_and_b32_e32 v70, 0xfffffff9, v64
	v_or3_b32 v94, v94, v95, v70
	v_lshl_add_u32 v94, v94, 2, s99
	s_lshr_b32 s98, s70, 1
	s_lshl_b32 s98, s98, 12
	s_and_b32 s99, s70, 1
	s_lshl_b32 s99, s99, 8
	s_add_i32 s98, s98, s99
	v_lshrrev_b32_e32 v69, 4, v64
	v_lshlrev_b32_e32 v69, 9, v69
	v_and_b32_e32 v70, 15, v64
	v_lshl_add_u32 v69, v70, 2, v69
	v_add_u32_e32 v69, s98, v69
	s_waitcnt lgkmcnt(7)
	v_add_f32_e32 v170, 0, v170
	v_add_f32_e32 v171, 0, v171
	s_waitcnt lgkmcnt(6)
	v_add_f32_e32 v172, v170, v172
	v_add_f32_e32 v173, v171, v173
	s_waitcnt lgkmcnt(5)
	v_add_f32_e32 v174, v172, v174
	v_add_f32_e32 v175, v173, v175
	s_waitcnt lgkmcnt(4)
	v_add_f32_e32 v176, v174, v176
	v_add_f32_e32 v177, v175, v177
	s_waitcnt lgkmcnt(3)
	v_add_f32_e32 v178, v176, v178
	v_add_f32_e32 v179, v177, v179
	s_waitcnt lgkmcnt(2)
	v_add_f32_e32 v180, v178, v180
	v_add_f32_e32 v181, v179, v181
	s_waitcnt lgkmcnt(1)
	v_add_f32_e32 v182, v180, v182
	v_add_f32_e32 v183, v181, v183
	s_waitcnt lgkmcnt(0)
	v_add_f32_e32 v184, v182, v184
	v_add_f32_e32 v185, v183, v185
	ds_write_b64 v66, v[184:185]
	s_waitcnt lgkmcnt(0)
	s_barrier
	ds_read_b64 v[72:73], v67
	ds_read_b64 v[74:75], v67 offset:512
	ds_read_b64 v[76:77], v67 offset:1024
	ds_read_b64 v[78:79], v67 offset:1536
	ds_read_b64 v[80:81], v67 offset:2048
	ds_read_b64 v[82:83], v67 offset:2560
	ds_read_b64 v[84:85], v67 offset:3072
	ds_read_b64 v[86:87], v67 offset:3584
	ds_read_b32 v202, v68
	ds_read_b32 v210, v68 offset:17408
	ds_read_b32 v203, v68 offset:272
	ds_read_b32 v211, v68 offset:17680
	ds_read_b32 v204, v68 offset:544
	ds_read_b32 v212, v68 offset:17952
	s_waitcnt lgkmcnt(6)
	ds_read_b32 v205, v68 offset:816
	ds_read_b32 v213, v68 offset:18224
	ds_read_b32 v206, v68 offset:1088
	ds_read_b32 v214, v68 offset:18496
	ds_read_b32 v207, v68 offset:1360
	ds_read_b32 v215, v68 offset:18768
	ds_read_b32 v208, v68 offset:1632
	ds_read_b32 v216, v68 offset:19040
	v_mul_f32_e32 v88, v238, v72
	v_mul_f32_e32 v89, v238, v73
	v_fmac_f32_e32 v88, v239, v74
	v_fmac_f32_e32 v89, v239, v75
	v_fmac_f32_e32 v88, v240, v76
	v_fmac_f32_e32 v89, v240, v77
	v_fmac_f32_e32 v88, v241, v78
	v_fmac_f32_e32 v89, v241, v79
	v_fmac_f32_e32 v88, v242, v80
	v_fmac_f32_e32 v89, v242, v81
	v_fmac_f32_e32 v88, v243, v82
	v_fmac_f32_e32 v89, v243, v83
	v_fmac_f32_e32 v88, v244, v84
	v_fmac_f32_e32 v89, v244, v85
	v_add_f32_e32 v90, v72, v74
	v_add_f32_e32 v91, v73, v75
	v_add_f32_e32 v90, v90, v76
	v_add_f32_e32 v91, v91, v77
	v_add_f32_e32 v90, v90, v78
	v_add_f32_e32 v91, v91, v79
	v_add_f32_e32 v90, v90, v80
	v_add_f32_e32 v91, v91, v81
	v_add_f32_e32 v90, v90, v82
	v_add_f32_e32 v91, v91, v83
	v_add_f32_e32 v90, v90, v84
	v_add_f32_e32 v91, v91, v85
	v_add_f32_e32 v90, v90, v86
	v_add_f32_e32 v91, v91, v87
	v_mul_f32_e32 v92, 0x3fb8aa3b, v90
	v_mul_f32_e32 v93, 0x3fb8aa3b, v91
	v_exp_f32_e32 v92, v92
	v_exp_f32_e32 v93, v93
	v_add_f32_e32 v170, v170, v88
	v_add_f32_e32 v171, v171, v89
	v_add_f32_e32 v172, v172, v88
	v_add_f32_e32 v173, v173, v89
	v_add_f32_e32 v174, v174, v88
	v_add_f32_e32 v175, v175, v89
	v_add_f32_e32 v176, v176, v88
	v_add_f32_e32 v177, v177, v89
	v_add_f32_e32 v178, v178, v88
	v_add_f32_e32 v179, v179, v89
	v_add_f32_e32 v180, v180, v88
	v_add_f32_e32 v181, v181, v89
	v_add_f32_e32 v182, v182, v88
	v_add_f32_e32 v183, v183, v89
	v_add_f32_e32 v184, v184, v88
	v_add_f32_e32 v185, v185, v89
	v_mul_f32_e32 v170, 0x3fb8aa3b, v170
	v_mul_f32_e32 v171, 0x3fb8aa3b, v171
	v_mul_f32_e32 v172, 0x3fb8aa3b, v172
	v_mul_f32_e32 v173, 0x3fb8aa3b, v173
	v_mul_f32_e32 v174, 0x3fb8aa3b, v174
	v_mul_f32_e32 v175, 0x3fb8aa3b, v175
	v_mul_f32_e32 v176, 0x3fb8aa3b, v176
	v_mul_f32_e32 v177, 0x3fb8aa3b, v177
	v_mul_f32_e32 v178, 0x3fb8aa3b, v178
	v_mul_f32_e32 v179, 0x3fb8aa3b, v179
	v_mul_f32_e32 v180, 0x3fb8aa3b, v180
	v_mul_f32_e32 v181, 0x3fb8aa3b, v181
	v_mul_f32_e32 v182, 0x3fb8aa3b, v182
	v_mul_f32_e32 v183, 0x3fb8aa3b, v183
	v_mul_f32_e32 v184, 0x3fb8aa3b, v184
	v_mul_f32_e32 v185, 0x3fb8aa3b, v185
	v_exp_f32_e32 v170, v170
	v_exp_f32_e32 v171, v171
	v_exp_f32_e32 v172, v172
	v_exp_f32_e32 v173, v173
	v_exp_f32_e32 v174, v174
	v_exp_f32_e32 v175, v175
	v_exp_f32_e32 v176, v176
	v_exp_f32_e32 v177, v177
	v_exp_f32_e32 v178, v178
	v_exp_f32_e32 v179, v179
	v_exp_f32_e32 v180, v180
	v_exp_f32_e32 v181, v181
	v_exp_f32_e32 v182, v182
	v_exp_f32_e32 v183, v183
	v_exp_f32_e32 v184, v184
	v_exp_f32_e32 v185, v185
	v_rcp_f32_e32 v186, v170
	v_rcp_f32_e32 v187, v171
	v_rcp_f32_e32 v188, v172
	v_rcp_f32_e32 v189, v173
	v_rcp_f32_e32 v190, v174
	v_rcp_f32_e32 v191, v175
	v_rcp_f32_e32 v192, v176
	v_rcp_f32_e32 v193, v177
	v_rcp_f32_e32 v194, v178
	v_rcp_f32_e32 v195, v179
	v_rcp_f32_e32 v196, v180
	v_rcp_f32_e32 v197, v181
	v_rcp_f32_e32 v198, v182
	v_rcp_f32_e32 v199, v183
	v_rcp_f32_e32 v200, v184
	v_rcp_f32_e32 v201, v185
	v_mul_f32_e32 v170, 0x3db504f3, v170
	v_mul_f32_e32 v171, 0x3db504f3, v171
	v_mul_f32_e32 v172, 0x3db504f3, v172
	v_mul_f32_e32 v173, 0x3db504f3, v173
	v_mul_f32_e32 v174, 0x3db504f3, v174
	v_mul_f32_e32 v175, 0x3db504f3, v175
	v_mul_f32_e32 v176, 0x3db504f3, v176
	v_mul_f32_e32 v177, 0x3db504f3, v177
	v_mul_f32_e32 v178, 0x3db504f3, v178
	v_mul_f32_e32 v179, 0x3db504f3, v179
	v_mul_f32_e32 v180, 0x3db504f3, v180
	v_mul_f32_e32 v181, 0x3db504f3, v181
	v_mul_f32_e32 v182, 0x3db504f3, v182
	v_mul_f32_e32 v183, 0x3db504f3, v183
	v_mul_f32_e32 v184, 0x3db504f3, v184
	v_mul_f32_e32 v185, 0x3db504f3, v185
	s_cmp_lg_u32 s70, 0
	s_cbranch_scc1 .Lscan_c2_nodl
	v_lshlrev_b32_e32 v70, 3, v64
	v_add_u32_e32 v70, 0x1fc00, v70
	ds_write_b64 v70, v[92:93]
; __device__ __forceinline__ int v_st(int k, int c) { const int kk = (k & ~0xC) | ((k & 4) << 1) | ((k & 8) >> 1); return ((kk >> 3) * 4 + (c >> 5)) * 512 + ((kk & 7) * 32 + (c & 31)) * 2; }
; __device__ __forceinline__ float bf2f(short s) { return __uint_as_float(((unsigned)(unsigned short)s) << 16); }
; __device__ __forceinline__ float bf2f(u16 u) { return __uint_as_float((unsigned)u << 16); }
; __device__ __forceinline__ u16 f2bf(float f) { return (u16)(pk2(f, 0.f) & 0xffffu); }
; __device__ __forceinline__ void scan_unit(const int unit, const Args& a, unsigned char* lds, const int mk_wid) {
;     ...
;           u16* qcol = qe + (g * 16) * QP + c; u16* kcol = ke + (g * 16) * QP + c; unsigned char* kdb = lds + L_KD + v_st(g * 16, c);
; #pragma unroll
;           for (int ii = 0; ii < 16; ++ii) { const float bb = bl[ii] + off;
;               const float qf = bf2f(qcol[ii * QP]), kf = bf2f(kcol[ii * QP]);
;               const float e = __builtin_amdgcn_exp2f(bb * 1.4426950408889634f), ker = kf * __builtin_amdgcn_rcpf(e);
;               qcol[ii * QP] = f2bf(qf * (0.088388347648318440f * e));
;               kcol[ii * QP] = f2bf(ker);
;               *(u16*)(kdb + v_st(ii, 0)) = f2bf(ker * dlc); } }
.Lscan_c2_nodl:
	v_mov_b32_e32 v71, 0xffff0000
	s_waitcnt lgkmcnt(12)
	v_lshlrev_b32_e32 v218, 16, v202
	v_and_b32_e32 v219, v71, v202
	v_lshlrev_b32_e32 v220, 16, v210
	v_and_b32_e32 v221, v71, v210
	v_mul_f32_e32 v218, v170, v218
	v_mul_f32_e32 v219, v171, v219
	v_mul_f32_e32 v220, v186, v220
	v_mul_f32_e32 v221, v187, v221
	v_cvt_pk_bf16_f32 v224, v218, v219
	v_mul_f32_e32 v222, v92, v220
	v_mul_f32_e32 v223, v93, v221
	v_cvt_pk_bf16_f32 v225, v220, v221
	ds_write_b32 v94, v224
	ds_write_b32 v94, v225 offset:17408
	v_cvt_pk_bf16_f32 v226, v222, v223
	ds_read_b32 v209, v68 offset:1904
	ds_read_b32 v217, v68 offset:19312
	ds_write_b32 v69, v226 offset:34816
	s_waitcnt lgkmcnt(15)
	v_lshlrev_b32_e32 v228, 16, v203
	v_and_b32_e32 v229, v71, v203
	v_lshlrev_b32_e32 v230, 16, v211
	v_and_b32_e32 v231, v71, v211
	v_mul_f32_e32 v228, v172, v228
	v_mul_f32_e32 v229, v173, v229
	v_mul_f32_e32 v230, v188, v230
	v_mul_f32_e32 v231, v189, v231
	v_cvt_pk_bf16_f32 v234, v228, v229
	v_mul_f32_e32 v232, v92, v230
	v_mul_f32_e32 v233, v93, v231
	v_cvt_pk_bf16_f32 v235, v230, v231
	ds_write_b32 v94, v234 offset:272
	ds_write_b32 v94, v235 offset:17680
	v_cvt_pk_bf16_f32 v236, v232, v233
	ds_write_b32 v69, v236 offset:34880
	s_waitcnt lgkmcnt(15)
	v_lshlrev_b32_e32 v218, 16, v204
	v_and_b32_e32 v219, v71, v204
	v_lshlrev_b32_e32 v220, 16, v212
	v_and_b32_e32 v221, v71, v212
	v_mul_f32_e32 v218, v174, v218
	v_mul_f32_e32 v219, v175, v219
	v_mul_f32_e32 v220, v190, v220
	v_mul_f32_e32 v221, v191, v221
	v_cvt_pk_bf16_f32 v224, v218, v219
	v_mul_f32_e32 v222, v92, v220
	v_mul_f32_e32 v223, v93, v221
	v_cvt_pk_bf16_f32 v225, v220, v221
	ds_write_b32 v94, v224 offset:544
	ds_write_b32 v94, v225 offset:17952
	v_cvt_pk_bf16_f32 v226, v222, v223
	ds_write_b32 v69, v226 offset:34944
	s_waitcnt lgkmcnt(15)
	v_lshlrev_b32_e32 v228, 16, v205
	v_and_b32_e32 v229, v71, v205
	v_lshlrev_b32_e32 v230, 16, v213
	v_and_b32_e32 v231, v71, v213
	v_mul_f32_e32 v228, v176, v228
	v_mul_f32_e32 v229, v177, v229
	v_mul_f32_e32 v230, v192, v230
	v_mul_f32_e32 v231, v193, v231
	v_cvt_pk_bf16_f32 v234, v228, v229
	v_mul_f32_e32 v232, v92, v230
	v_mul_f32_e32 v233, v93, v231
	v_cvt_pk_bf16_f32 v235, v230, v231
	ds_write_b32 v94, v234 offset:816
	ds_write_b32 v94, v235 offset:18224
	v_cvt_pk_bf16_f32 v236, v232, v233
	ds_write_b32 v69, v236 offset:35008
	s_waitcnt lgkmcnt(15)
	v_lshlrev_b32_e32 v218, 16, v206
	v_and_b32_e32 v219, v71, v206
	v_lshlrev_b32_e32 v220, 16, v214
	v_and_b32_e32 v221, v71, v214
	v_mul_f32_e32 v218, v178, v218
	v_mul_f32_e32 v219, v179, v219
	v_mul_f32_e32 v220, v194, v220
	v_mul_f32_e32 v221, v195, v221
	v_cvt_pk_bf16_f32 v224, v218, v219
	v_mul_f32_e32 v222, v92, v220
	v_mul_f32_e32 v223, v93, v221
	v_cvt_pk_bf16_f32 v225, v220, v221
	ds_write_b32 v94, v224 offset:1088
	ds_write_b32 v94, v225 offset:18496
	v_cvt_pk_bf16_f32 v226, v222, v223
	ds_write_b32 v69, v226 offset:36864
	s_waitcnt lgkmcnt(15)
	v_lshlrev_b32_e32 v228, 16, v207
	v_and_b32_e32 v229, v71, v207
	v_lshlrev_b32_e32 v230, 16, v215
	v_and_b32_e32 v231, v71, v215
	v_mul_f32_e32 v228, v180, v228
	v_mul_f32_e32 v229, v181, v229
	v_mul_f32_e32 v230, v196, v230
	v_mul_f32_e32 v231, v197, v231
	v_cvt_pk_bf16_f32 v234, v228, v229
	v_mul_f32_e32 v232, v92, v230
	v_mul_f32_e32 v233, v93, v231
	v_cvt_pk_bf16_f32 v235, v230, v231
	ds_write_b32 v94, v234 offset:1360
	ds_write_b32 v94, v235 offset:18768
	v_cvt_pk_bf16_f32 v236, v232, v233
	ds_write_b32 v69, v236 offset:36928
	s_waitcnt lgkmcnt(15)
	v_lshlrev_b32_e32 v218, 16, v208
	v_and_b32_e32 v219, v71, v208
	v_lshlrev_b32_e32 v220, 16, v216
	v_and_b32_e32 v221, v71, v216
	v_mul_f32_e32 v218, v182, v218
	v_mul_f32_e32 v219, v183, v219
	v_mul_f32_e32 v220, v198, v220
	v_mul_f32_e32 v221, v199, v221
	v_cvt_pk_bf16_f32 v224, v218, v219
	v_mul_f32_e32 v222, v92, v220
	v_mul_f32_e32 v223, v93, v221
	v_cvt_pk_bf16_f32 v225, v220, v221
	ds_write_b32 v94, v224 offset:1632
	ds_write_b32 v94, v225 offset:19040
	v_cvt_pk_bf16_f32 v226, v222, v223
	ds_write_b32 v69, v226 offset:36992
	s_waitcnt lgkmcnt(15)
	v_lshlrev_b32_e32 v228, 16, v209
	v_and_b32_e32 v229, v71, v209
	v_lshlrev_b32_e32 v230, 16, v217
	v_and_b32_e32 v231, v71, v217
	v_mul_f32_e32 v228, v184, v228
	v_mul_f32_e32 v229, v185, v229
	v_mul_f32_e32 v230, v200, v230
	v_mul_f32_e32 v231, v201, v231
	v_cvt_pk_bf16_f32 v234, v228, v229
	v_mul_f32_e32 v232, v92, v230
	v_mul_f32_e32 v233, v93, v231
	v_cvt_pk_bf16_f32 v235, v230, v231
	ds_write_b32 v94, v234 offset:1904
	ds_write_b32 v94, v235 offset:19312
	v_cvt_pk_bf16_f32 v236, v232, v233
	ds_write_b32 v69, v236 offset:37056
	s_add_i32 s58, s5, 1
	s_cmp_eq_u32 s50, 3
	s_cbranch_scc1 .LBB0_435
	v_mbcnt_lo_u32_b32 v64, -1, 0
	v_mbcnt_hi_u32_b32 v64, -1, v64
	s_andn2_b64 vcc, exec, s[6:7]
	v_add_u32_e32 v70, s72, v64
	s_mov_b32 s34, s58
	s_cbranch_vccnz .LBB0_426
	s_cmp_gt_u32 s5, 2
	s_mov_b32 s34, s50
	s_cbranch_scc1 .LBB0_426
	s_sub_i32 s34, 2, s5

; __device__ __forceinline__ void scan_unit(const int unit, const Args& a, unsigned char* lds, const int mk_wid) {
;     ...
;               f32x16 o0 = f32x16{}, o1 = f32x16{};
; #pragma unroll
;               for (int ct = 0; ct < 4; ++ct)
; #pragma unroll
;                 for (int kb = 0; kb < 2; ++kb) { const int cb = ct * 32 + kb * 16;
;                     v4u sw; sw.x = pk2(S[ct][8 * kb + 0], S[ct][8 * kb + 1]); sw.y = pk2(S[ct][8 * kb + 2], S[ct][8 * kb + 3]); sw.z = pk2(S[ct][8 * kb + 4], S[ct][8 * kb + 5]); sw.w = pk2(S[ct][8 * kb + 6], S[ct][8 * kb + 7]);
;                     const bf16x8 sb = __builtin_bit_cast(bf16x8, sw);
;                     { const u16* p0 = qe + r32 * QP + cb + 4 * hi; const v2u lo = *(const v2u*)p0, hh = *(const v2u*)(p0 + 8); v4u aw = {lo.x, lo.y, hh.x, hh.y};
;                       o0 = __builtin_amdgcn_mfma_f32_32x32x16_bf16(__builtin_bit_cast(bf16x8, aw), sb, o0, 0, 0, 0); }
;                     { const u16* p1 = qe + (32 + r32) * QP + cb + 4 * hi; const v2u lo = *(const v2u*)p1, hh = *(const v2u*)(p1 + 8); v4u aw = {lo.x, lo.y, hh.x, hh.y};
;                       o1 = __builtin_amdgcn_mfma_f32_32x32x16_bf16(__builtin_bit_cast(bf16x8, aw), sb, o1, 0, 0, 0); } }
;               GLA_LOADV();
;               asm volatile("s_waitcnt lgkmcnt(0)" ::: "memory"); GLA_SBAR();
;               { const u16* a0 = am + r32 * AP + hi * 8; const u16* a1 = am + (32 + r32) * AP + hi * 8;
;                 o0 = __builtin_amdgcn_mfma_f32_32x32x16_bf16(*(const bf16x8*)(a0), GLA_PK(vl0, vh0), o0, 0, 0, 0);
;                 o0 = __builtin_amdgcn_mfma_f32_32x32x16_bf16(*(const bf16x8*)(a0 + 16), GLA_PK(vl1, vh1), o0, 0, 0, 0);
;                 o1 = __builtin_amdgcn_mfma_f32_32x32x16_bf16(*(const bf16x8*)(a1), GLA_PK(vl0, vh0), o1, 0, 0, 0);
;                 o1 = __builtin_amdgcn_mfma_f32_32x32x16_bf16(*(const bf16x8*)(a1 + 16), GLA_PK(vl1, vh1), o1, 0, 0, 0);
;                 o1 = __builtin_amdgcn_mfma_f32_32x32x16_bf16(*(const bf16x8*)(a1 + 32), GLA_PK(vl2, vh2), o1, 0, 0, 0);
;                 o1 = __builtin_amdgcn_mfma_f32_32x32x16_bf16(*(const bf16x8*)(a1 + 48), GLA_PK(vl3, vh3), o1, 0, 0, 0); }
;               { u16* ow = ot + (4 * hi) * 256 + vt * 32 + r32;
; #pragma unroll
;                 for (int r = 0; r < 16; ++r) { const int i0 = crow(r, 0); ow[i0 * 256] = f2bf(o0[r]); ow[(i0 + 32) * 256] = f2bf(o1[r]); } }
.LBB0_442:
	v_and_b32_e32 v168, 31, v64
	v_mul_u32_u24_e32 v64, 0x110, v168
	v_lshlrev_b32_e32 v65, 4, v157
	v_add3_u32 v144, 0, v64, v65
	ds_read_b128 v[170:173], v144
	ds_read_b128 v[174:177], v144 offset:32
	ds_read_b128 v[178:181], v144 offset:8704
	ds_read_b128 v[182:185], v144 offset:8736
	ds_read_b128 v[186:189], v144 offset:64
	ds_read_b128 v[190:193], v144 offset:8768
	ds_read_b128 v[194:197], v144 offset:96
	ds_read_b128 v[198:201], v144 offset:8800
	ds_read_b128 v[202:205], v144 offset:128
	ds_read_b128 v[206:209], v144 offset:8832
	ds_read_b128 v[210:213], v144 offset:160
	ds_read_b128 v[214:217], v144 offset:8864
	ds_read_b128 v[218:221], v144 offset:192
	ds_read_b128 v[222:225], v144 offset:8896
	ds_read_b128 v[226:229], v144 offset:224
	v_cvt_pk_bf16_f32 v80, v0, v1
	v_cvt_pk_bf16_f32 v81, v2, v3
	v_cvt_pk_bf16_f32 v82, v4, v5
	v_cvt_pk_bf16_f32 v83, v6, v7
	s_waitcnt lgkmcnt(14)
	s_nop 0
	v_mfma_f32_32x32x16_bf16 v[64:79], v[170:173], v[80:83], 0
	ds_read_b128 v[230:233], v144 offset:8928
	v_cvt_pk_bf16_f32 v140, v8, v9
	v_cvt_pk_bf16_f32 v141, v10, v11
	v_cvt_pk_bf16_f32 v142, v12, v13
	v_cvt_pk_bf16_f32 v143, v14, v15
	v_cvt_pk_bf16_f32 v160, v56, v57
	v_cvt_pk_bf16_f32 v161, v58, v59
	v_cvt_pk_bf16_f32 v162, v60, v61
	v_cvt_pk_bf16_f32 v163, v62, v63
	s_waitcnt lgkmcnt(14)
	s_nop 0
	v_mfma_f32_32x32x16_bf16 v[64:79], v[174:177], v[140:143], v[64:79]
	s_waitcnt lgkmcnt(13)
	v_mfma_f32_32x32x16_bf16 v[80:95], v[178:181], v[80:83], 0
	s_waitcnt lgkmcnt(12)
	v_mfma_f32_32x32x16_bf16 v[80:95], v[182:185], v[140:143], v[80:95]
	v_cvt_pk_bf16_f32 v140, v16, v17
	v_cvt_pk_bf16_f32 v141, v18, v19
	v_cvt_pk_bf16_f32 v142, v20, v21
	v_cvt_pk_bf16_f32 v143, v22, v23
	s_waitcnt lgkmcnt(11)
	s_nop 0
	v_mfma_f32_32x32x16_bf16 v[64:79], v[186:189], v[140:143], v[64:79]
	s_waitcnt lgkmcnt(10)
	v_mfma_f32_32x32x16_bf16 v[80:95], v[190:193], v[140:143], v[80:95]
	v_cvt_pk_bf16_f32 v140, v24, v25
	v_cvt_pk_bf16_f32 v141, v26, v27
	v_cvt_pk_bf16_f32 v142, v28, v29
	v_cvt_pk_bf16_f32 v143, v30, v31
	s_waitcnt lgkmcnt(9)
	s_nop 0
	v_mfma_f32_32x32x16_bf16 v[64:79], v[194:197], v[140:143], v[64:79]
	s_waitcnt lgkmcnt(8)
	v_mfma_f32_32x32x16_bf16 v[80:95], v[198:201], v[140:143], v[80:95]
	v_cvt_pk_bf16_f32 v140, v32, v33
	v_cvt_pk_bf16_f32 v141, v34, v35
	v_cvt_pk_bf16_f32 v142, v36, v37
	v_cvt_pk_bf16_f32 v143, v38, v39
	s_waitcnt lgkmcnt(7)
	s_nop 0
	v_mfma_f32_32x32x16_bf16 v[64:79], v[202:205], v[140:143], v[64:79]
	s_waitcnt lgkmcnt(6)
	v_mfma_f32_32x32x16_bf16 v[80:95], v[206:209], v[140:143], v[80:95]
	v_cvt_pk_bf16_f32 v140, v40, v41
	v_cvt_pk_bf16_f32 v141, v42, v43
	v_cvt_pk_bf16_f32 v142, v44, v45
	v_cvt_pk_bf16_f32 v143, v46, v47
	s_waitcnt lgkmcnt(5)
	s_nop 0
	v_mfma_f32_32x32x16_bf16 v[64:79], v[210:213], v[140:143], v[64:79]
	s_waitcnt lgkmcnt(4)
	v_mfma_f32_32x32x16_bf16 v[80:95], v[214:217], v[140:143], v[80:95]
	v_cvt_pk_bf16_f32 v140, v48, v49
	v_cvt_pk_bf16_f32 v141, v50, v51
	v_cvt_pk_bf16_f32 v142, v52, v53
	v_cvt_pk_bf16_f32 v143, v54, v55
	s_waitcnt lgkmcnt(3)
	s_nop 0
	v_mfma_f32_32x32x16_bf16 v[64:79], v[218:221], v[140:143], v[64:79]
	s_waitcnt lgkmcnt(2)
	v_mfma_f32_32x32x16_bf16 v[80:95], v[222:225], v[140:143], v[80:95]
	ds_read_b64_tr_b16 v[136:137], v158 offset:0
	s_waitcnt lgkmcnt(2)
	v_mfma_f32_32x32x16_bf16 v[64:79], v[226:229], v[160:163], v[64:79]
	ds_read_b64_tr_b16 v[138:139], v158 offset:0x800
	ds_read_b64_tr_b16 v[140:141], v158 offset:0x1000
	ds_read_b64_tr_b16 v[142:143], v158 offset:0x1800
	ds_read_b64_tr_b16 v[144:145], v158 offset:0x2000
	ds_read_b64_tr_b16 v[146:147], v158 offset:0x2800
	ds_read_b64_tr_b16 v[148:149], v158 offset:0x3000
	ds_read_b64_tr_b16 v[150:151], v158 offset:0x3800
	s_waitcnt lgkmcnt(0)
	v_mfma_f32_32x32x16_bf16 v[80:95], v[230:233], v[160:163], v[80:95]
	v_mul_u32_u24_e32 v158, 0x90, v168
	v_lshlrev_b32_e32 v159, 4, v157
	v_add3_u32 v166, s57, v158, v159
	ds_read_b128 v[158:161], v166
	ds_read_b128 v[162:165], v166 offset:32
	s_mov_b32 s34, s42
	s_waitcnt lgkmcnt(1)
	v_mfma_f32_32x32x16_bf16 v[64:79], v[158:161], v[136:139], v[64:79]
	s_waitcnt lgkmcnt(0)
	v_mfma_f32_32x32x16_bf16 v[64:79], v[162:165], v[140:143], v[64:79]
	ds_read_b128 v[158:161], v166 offset:4608
	ds_read_b128 v[162:165], v166 offset:4640
	s_waitcnt lgkmcnt(1)
	v_mfma_f32_32x32x16_bf16 v[80:95], v[158:161], v[136:139], v[80:95]
	s_nop 7
	v_cvt_pk_bf16_f32 v64, v64, s0
	s_waitcnt lgkmcnt(0)
	v_mfma_f32_32x32x16_bf16 v[80:95], v[162:165], v[140:143], v[80:95]
	ds_read_b128 v[158:161], v166 offset:4672
	ds_read_b128 v[162:165], v166 offset:4704
	s_waitcnt lgkmcnt(1)
	v_mfma_f32_32x32x16_bf16 v[80:95], v[158:161], v[144:147], v[80:95]
	v_lshlrev_b32_e32 v158, 11, v157
	v_lshlrev_b32_e32 v159, 1, v168
	v_add3_u32 v158, s49, v158, v159
	ds_write_b16 v158, v64
	s_waitcnt lgkmcnt(1)
	v_mfma_f32_32x32x16_bf16 v[80:95], v[162:165], v[148:151], v[80:95]
	s_nop 11
	v_cvt_pk_bf16_f32 v64, v80, s0
	ds_write_b16 v158, v64 offset:16384
	v_cvt_pk_bf16_f32 v64, v65, s0
	ds_write_b16 v158, v64 offset:512
	v_cvt_pk_bf16_f32 v64, v81, s0
	ds_write_b16 v158, v64 offset:16896
	v_cvt_pk_bf16_f32 v64, v66, s0
	ds_write_b16 v158, v64 offset:1024
	v_cvt_pk_bf16_f32 v64, v82, s0
	ds_write_b16 v158, v64 offset:17408
	v_cvt_pk_bf16_f32 v64, v67, s0
	ds_write_b16 v158, v64 offset:1536
	v_cvt_pk_bf16_f32 v64, v83, s0
	ds_write_b16 v158, v64 offset:17920
	v_cvt_pk_bf16_f32 v64, v68, s0
	ds_write_b16 v158, v64 offset:4096
	v_cvt_pk_bf16_f32 v64, v84, s0
	ds_write_b16 v158, v64 offset:20480
	v_cvt_pk_bf16_f32 v64, v69, s0
	ds_write_b16 v158, v64 offset:4608
	v_cvt_pk_bf16_f32 v64, v85, s0
	ds_write_b16 v158, v64 offset:20992
	v_cvt_pk_bf16_f32 v64, v70, s0
	ds_write_b16 v158, v64 offset:5120
	v_cvt_pk_bf16_f32 v64, v86, s0
	ds_write_b16 v158, v64 offset:21504
	v_cvt_pk_bf16_f32 v64, v71, s0
	ds_write_b16 v158, v64 offset:5632
	v_cvt_pk_bf16_f32 v64, v87, s0
	ds_write_b16 v158, v64 offset:22016
	v_cvt_pk_bf16_f32 v64, v72, s0
	ds_write_b16 v158, v64 offset:8192
	v_cvt_pk_bf16_f32 v64, v88, s0
	ds_write_b16 v158, v64 offset:24576
	v_cvt_pk_bf16_f32 v64, v73, s0
	ds_write_b16 v158, v64 offset:8704
	v_cvt_pk_bf16_f32 v64, v89, s0
	ds_write_b16 v158, v64 offset:25088
	v_cvt_pk_bf16_f32 v64, v74, s0
	ds_write_b16 v158, v64 offset:9216
	v_cvt_pk_bf16_f32 v64, v90, s0
	ds_write_b16 v158, v64 offset:25600
	v_cvt_pk_bf16_f32 v64, v75, s0
	ds_write_b16 v158, v64 offset:9728
	v_cvt_pk_bf16_f32 v64, v91, s0
	ds_write_b16 v158, v64 offset:26112
	v_cvt_pk_bf16_f32 v64, v76, s0
	ds_write_b16 v158, v64 offset:12288
	v_cvt_pk_bf16_f32 v64, v92, s0
	ds_write_b16 v158, v64 offset:28672
	v_cvt_pk_bf16_f32 v64, v77, s0
	ds_write_b16 v158, v64 offset:12800
	v_cvt_pk_bf16_f32 v64, v93, s0
	ds_write_b16 v158, v64 offset:29184
	v_cvt_pk_bf16_f32 v64, v78, s0
	ds_write_b16 v158, v64 offset:13312
	v_cvt_pk_bf16_f32 v64, v94, s0
	ds_write_b16 v158, v64 offset:29696
	v_cvt_pk_bf16_f32 v64, v79, s0
	ds_write_b16 v158, v64 offset:13824
	v_cvt_pk_bf16_f32 v64, v95, s0
	ds_write_b16 v158, v64 offset:30208
; __device__ __forceinline__ int v_rd_base(int lane) { return ((lane & 3) << 3) | (((lane >> 2) & 3) << 6) | (((lane >> 4) & 1) << 5) | (((lane >> 5) & 1) << 8); }
; #define GLA_SBAR() __builtin_amdgcn_sched_barrier(0)
; __device__ __forceinline__ void scan_unit(const int unit, const Args& a, unsigned char* lds, const int mk_wid) {
;     ...
; #pragma unroll
;           for (int ct = 0; ct < 4; ++ct) { const int kb_ = ldsb + L_KD + v_rd_base(lane) + ct * 512;
;               const s16x4 al0 = tr_read<v_rd_off(0, 0, 0)>(kb_), ah0 = tr_read<v_rd_off(0, 0, 1)>(kb_), al1 = tr_read<v_rd_off(0, 1, 0)>(kb_), ah1 = tr_read<v_rd_off(0, 1, 1)>(kb_);
;               const s16x4 al2 = tr_read<v_rd_off(0, 2, 0)>(kb_), ah2 = tr_read<v_rd_off(0, 2, 1)>(kb_), al3 = tr_read<v_rd_off(0, 3, 0)>(kb_), ah3 = tr_read<v_rd_off(0, 3, 1)>(kb_);
;               const float* dp = dl + ct * 32 + 4 * hi;
; #pragma unroll
;               for (int rg = 0; rg < 4; ++rg) { const f32x4 d4 = *(const f32x4*)(dp + 8 * rg);
;                   S[ct][4 * rg + 0] *= d4.x; S[ct][4 * rg + 1] *= d4.y; S[ct][4 * rg + 2] *= d4.z; S[ct][4 * rg + 3] *= d4.w; }
;               asm volatile("s_waitcnt lgkmcnt(0)" ::: "memory"); GLA_SBAR();
;               S[ct] = __builtin_amdgcn_mfma_f32_32x32x16_bf16(GLA_PK(al0, ah0), GLA_PK(vl0, vh0), S[ct], 0, 0, 0);
;               S[ct] = __builtin_amdgcn_mfma_f32_32x32x16_bf16(GLA_PK(al1, ah1), GLA_PK(vl1, vh1), S[ct], 0, 0, 0);
;               S[ct] = __builtin_amdgcn_mfma_f32_32x32x16_bf16(GLA_PK(al2, ah2), GLA_PK(vl2, vh2), S[ct], 0, 0, 0);
;               S[ct] = __builtin_amdgcn_mfma_f32_32x32x16_bf16(GLA_PK(al3, ah3), GLA_PK(vl3, vh3), S[ct], 0, 0, 0); } }
;         __syncthreads();
;         pend_cc = lat ? cc : -1;
.LBB0_443:
	s_cmp_lg_u32 0, -1
	s_cselect_b32 s4, 0, 0
	s_add_i32 s5, s4, 0x8800
	v_lshl_add_u32 v64, v157, 4, 0
	v_add_u32_e32 v80, s5, v154
	v_add_u32_e32 v157, 0x1fc00, v64
	ds_read_b64_tr_b16 v[64:65], v80 offset:0
	ds_read_b64_tr_b16 v[66:67], v80 offset:0x800
	ds_read_b64_tr_b16 v[68:69], v80 offset:0x1000
	ds_read_b64_tr_b16 v[70:71], v80 offset:0x1800
	ds_read_b64_tr_b16 v[72:73], v80 offset:0x2000
	ds_read_b64_tr_b16 v[74:75], v80 offset:0x2800
	ds_read_b64_tr_b16 v[76:77], v80 offset:0x3000
	ds_read_b64_tr_b16 v[78:79], v80 offset:0x3800
	ds_read_b128 v[80:83], v157
	ds_read_b128 v[84:87], v157 offset:32
	ds_read_b128 v[88:91], v157 offset:64
	s_waitcnt lgkmcnt(2)
	v_pk_mul_f32 v[0:1], v[0:1], v[80:81]
	v_pk_mul_f32 v[2:3], v[2:3], v[82:83]
	ds_read_b128 v[80:83], v157 offset:96
	s_waitcnt lgkmcnt(0)
	s_waitcnt lgkmcnt(2)
	v_pk_mul_f32 v[4:5], v[4:5], v[84:85]
	v_pk_mul_f32 v[6:7], v[6:7], v[86:87]
	s_waitcnt lgkmcnt(1)
	v_pk_mul_f32 v[8:9], v[8:9], v[88:89]
	v_pk_mul_f32 v[10:11], v[10:11], v[90:91]
	s_waitcnt lgkmcnt(0)
	v_pk_mul_f32 v[12:13], v[12:13], v[80:81]
	v_pk_mul_f32 v[14:15], v[14:15], v[82:83]
	s_nop 1
	v_mfma_f32_32x32x16_bf16 v[0:15], v[64:67], v[136:139], v[0:15]
	s_add_i32 s5, s4, 0x8a00
	v_add_u32_e32 v88, s5, v154
	ds_read_b64_tr_b16 v[64:65], v88 offset:0
	ds_read_b64_tr_b16 v[66:67], v88 offset:0x800
	ds_read_b64_tr_b16 v[80:81], v88 offset:0x1000
	ds_read_b64_tr_b16 v[82:83], v88 offset:0x1800
	ds_read_b64_tr_b16 v[84:85], v88 offset:0x2000
	v_mfma_f32_32x32x16_bf16 v[0:15], v[68:71], v[140:143], v[0:15]
	ds_read_b64_tr_b16 v[86:87], v88 offset:0x2800
	ds_read_b64_tr_b16 v[68:69], v88 offset:0x3000
	ds_read_b64_tr_b16 v[70:71], v88 offset:0x3800
	ds_read_b128 v[88:91], v157 offset:128
	ds_read_b128 v[92:95], v157 offset:160
	s_waitcnt lgkmcnt(1)
	v_mul_f32_e64 v16, v16, v88
	v_mul_f32_e64 v17, v17, v89
	v_mfma_f32_32x32x16_bf16 v[0:15], v[72:75], v[144:147], v[0:15]
	v_mul_f32_e64 v18, v18, v90
	v_mul_f32_e64 v19, v19, v91
	ds_read_b128 v[88:91], v157 offset:192
	ds_read_b128 v[72:75], v157 offset:224
	s_waitcnt lgkmcnt(0)
	s_waitcnt lgkmcnt(2)
	v_pk_mul_f32 v[20:21], v[20:21], v[92:93]
	v_pk_mul_f32 v[22:23], v[22:23], v[94:95]
	s_waitcnt lgkmcnt(1)
	v_pk_mul_f32 v[24:25], v[24:25], v[88:89]
	v_mfma_f32_32x32x16_bf16 v[0:15], v[76:79], v[148:151], v[0:15]
	v_mul_f32_e64 v26, v26, v90
	v_mul_f32_e64 v27, v27, v91
	s_waitcnt lgkmcnt(0)
	v_mul_f32_e64 v28, v28, v72
	v_mul_f32_e64 v29, v29, v73
	v_pk_mul_f32 v[30:31], v[30:31], v[74:75]
	s_nop 1
	v_mfma_f32_32x32x16_bf16 v[16:31], v[64:67], v[136:139], v[16:31]
	s_add_i32 s5, s4, 0x8c00
	v_add_u32_e32 v88, s5, v154
	ds_read_b64_tr_b16 v[64:65], v88 offset:0
	ds_read_b64_tr_b16 v[66:67], v88 offset:0x800
	ds_read_b64_tr_b16 v[72:73], v88 offset:0x1000
	ds_read_b64_tr_b16 v[74:75], v88 offset:0x1800
	ds_read_b64_tr_b16 v[76:77], v88 offset:0x2000
	v_mfma_f32_32x32x16_bf16 v[16:31], v[80:83], v[140:143], v[16:31]
	ds_read_b64_tr_b16 v[78:79], v88 offset:0x2800
	ds_read_b64_tr_b16 v[80:81], v88 offset:0x3000
	ds_read_b64_tr_b16 v[82:83], v88 offset:0x3800
	ds_read_b128 v[88:91], v157 offset:256
	ds_read_b128 v[92:95], v157 offset:288
	s_waitcnt lgkmcnt(1)
	v_mul_f32_e64 v32, v32, v88
	v_mul_f32_e64 v33, v33, v89
	v_mfma_f32_32x32x16_bf16 v[16:31], v[84:87], v[144:147], v[16:31]
	v_mul_f32_e64 v34, v34, v90
	v_mul_f32_e64 v35, v35, v91
	ds_read_b128 v[88:91], v157 offset:320
	ds_read_b128 v[84:87], v157 offset:352
	s_waitcnt lgkmcnt(0)
	s_waitcnt lgkmcnt(2)
	v_pk_mul_f32 v[36:37], v[36:37], v[92:93]
	v_pk_mul_f32 v[38:39], v[38:39], v[94:95]
	s_waitcnt lgkmcnt(1)
	v_pk_mul_f32 v[40:41], v[40:41], v[88:89]
	v_mfma_f32_32x32x16_bf16 v[16:31], v[68:71], v[148:151], v[16:31]
	v_mul_f32_e64 v42, v42, v90
	v_mul_f32_e64 v43, v43, v91
	s_waitcnt lgkmcnt(0)
	v_mul_f32_e64 v44, v44, v84
	v_mul_f32_e64 v45, v45, v85
	v_pk_mul_f32 v[46:47], v[46:47], v[86:87]
	s_nop 1
	v_mfma_f32_32x32x16_bf16 v[32:47], v[64:67], v[136:139], v[32:47]
	s_add_i32 s4, s4, 0x8e00
	v_add_u32_e32 v88, s4, v154
	ds_read_b64_tr_b16 v[64:65], v88 offset:0
	ds_read_b64_tr_b16 v[66:67], v88 offset:0x800
	ds_read_b64_tr_b16 v[68:69], v88 offset:0x1000
	ds_read_b64_tr_b16 v[70:71], v88 offset:0x1800
	ds_read_b64_tr_b16 v[84:85], v88 offset:0x2000
	v_mfma_f32_32x32x16_bf16 v[32:47], v[72:75], v[140:143], v[32:47]
	ds_read_b64_tr_b16 v[86:87], v88 offset:0x2800
	ds_read_b64_tr_b16 v[72:73], v88 offset:0x3000
	ds_read_b64_tr_b16 v[74:75], v88 offset:0x3800
	ds_read_b128 v[88:91], v157 offset:384
	ds_read_b128 v[92:95], v157 offset:416
	s_waitcnt lgkmcnt(1)
	v_mul_f32_e64 v48, v48, v88
	v_mul_f32_e64 v49, v49, v89
	v_mfma_f32_32x32x16_bf16 v[32:47], v[76:79], v[144:147], v[32:47]
	v_mul_f32_e64 v50, v50, v90
	v_mul_f32_e64 v51, v51, v91
	ds_read_b128 v[88:91], v157 offset:448
	ds_read_b128 v[76:79], v157 offset:480
	s_waitcnt lgkmcnt(0)
	s_waitcnt lgkmcnt(2)
	v_pk_mul_f32 v[52:53], v[52:53], v[92:93]
	v_pk_mul_f32 v[54:55], v[54:55], v[94:95]
	s_waitcnt lgkmcnt(1)
	v_pk_mul_f32 v[56:57], v[56:57], v[88:89]
	v_mfma_f32_32x32x16_bf16 v[32:47], v[80:83], v[148:151], v[32:47]
	v_mul_f32_e64 v58, v58, v90
	v_mul_f32_e64 v59, v59, v91
	s_waitcnt lgkmcnt(0)
	v_mul_f32_e64 v60, v60, v76
	v_mul_f32_e64 v61, v61, v77
	v_pk_mul_f32 v[62:63], v[62:63], v[78:79]
	s_nop 1
	v_mfma_f32_32x32x16_bf16 v[48:63], v[64:67], v[136:139], v[48:63]
	s_add_i32 s50, s50, -1
	s_cmp_eq_u32 s50, 2
	s_barrier
	v_mfma_f32_32x32x16_bf16 v[48:63], v[68:71], v[140:143], v[48:63]
	v_mfma_f32_32x32x16_bf16 v[48:63], v[84:87], v[144:147], v[48:63]
	v_mfma_f32_32x32x16_bf16 v[48:63], v[72:75], v[148:151], v[48:63]
	s_cbranch_scc1 .LBB0_447
	s_mov_b32 s5, s58
	s_branch .LBB0_418
